# SwiGLU epilogue of the gate/up GEMM rescheduled: 4 independent element chains interleaved, trans-op s_nops removed (on top of pipelined conversion)
# baseline (speedup 1.0000x reference)
.LBB0_1063:
	v_mul_f32_e32 v146, 0xbfb8aa3b, v126
	v_mul_f32_e32 v147, 0xbfb8aa3b, v127
	v_mul_f32_e32 v148, 0xbfb8aa3b, v128
	v_mul_f32_e32 v149, 0xbfb8aa3b, v129
	v_exp_f32_e32 v146, v146
	v_exp_f32_e32 v147, v147
	v_exp_f32_e32 v148, v148
	v_exp_f32_e32 v149, v149
	v_add_f32_e32 v146, 1.0, v146
	v_add_f32_e32 v147, 1.0, v147
	v_add_f32_e32 v148, 1.0, v148
	v_add_f32_e32 v149, 1.0, v149
	v_rcp_f32_e32 v146, v146
	v_rcp_f32_e32 v147, v147
	v_rcp_f32_e32 v148, v148
	v_rcp_f32_e32 v149, v149
	v_mul_f32_e32 v146, v126, v146
	v_mul_f32_e32 v147, v127, v147
	v_mul_f32_e32 v148, v128, v148
	v_mul_f32_e32 v149, v129, v149
	v_mul_f32_e32 v122, v146, v122
	v_mul_f32_e32 v123, v147, v123
	v_mul_f32_e32 v124, v148, v124
	v_mul_f32_e32 v125, v149, v125
	v_mul_f32_e32 v146, 0xbfb8aa3b, v118
	v_mul_f32_e32 v147, 0xbfb8aa3b, v119
	v_mul_f32_e32 v148, 0xbfb8aa3b, v120
	v_mul_f32_e32 v149, 0xbfb8aa3b, v121
	v_exp_f32_e32 v146, v146
	v_exp_f32_e32 v147, v147
	v_exp_f32_e32 v148, v148
	v_exp_f32_e32 v149, v149
	v_add_f32_e32 v146, 1.0, v146
	v_add_f32_e32 v147, 1.0, v147
	v_add_f32_e32 v148, 1.0, v148
	v_add_f32_e32 v149, 1.0, v149
	v_rcp_f32_e32 v146, v146
	v_rcp_f32_e32 v147, v147
	v_rcp_f32_e32 v148, v148
	v_rcp_f32_e32 v149, v149
	v_mul_f32_e32 v146, v118, v146
	v_mul_f32_e32 v147, v119, v147
	v_mul_f32_e32 v148, v120, v148
	v_mul_f32_e32 v149, v121, v149
	v_mul_f32_e32 v114, v146, v114
	v_mul_f32_e32 v115, v147, v115
	v_mul_f32_e32 v116, v148, v116
	v_mul_f32_e32 v117, v149, v117
	v_lshl_or_b32 v142, s25, 7, v139
	v_lshl_add_u32 v141, s24, 8, v137
	v_ashrrev_i32_e32 v143, 31, v142
	s_andn2_b64 vcc, exec, s[4:5]
	v_cvt_pk_bf16_f32 v118, v122, v123
	v_cvt_pk_bf16_f32 v119, v124, v125
	v_cvt_pk_bf16_f32 v120, v114, v115
	v_mov_b64_e32 v[114:115], s[10:11]
	v_cvt_pk_bf16_f32 v121, v116, v117
	v_mad_i64_i32 v[122:123], s[24:25], v141, s53, v[114:115]
	v_lshlrev_b64 v[116:117], 1, v[142:143]
	v_lshl_add_u64 v[122:123], v[122:123], 0, v[116:117]
	global_store_dwordx4 v[122:123], v[118:121], off
	s_nop 1
	v_mul_f32_e32 v146, 0xbfb8aa3b, v110
	v_mul_f32_e32 v147, 0xbfb8aa3b, v111
	v_mul_f32_e32 v148, 0xbfb8aa3b, v112
	v_mul_f32_e32 v149, 0xbfb8aa3b, v113
	v_exp_f32_e32 v146, v146
	v_exp_f32_e32 v147, v147
	v_exp_f32_e32 v148, v148
	v_exp_f32_e32 v149, v149
	v_add_f32_e32 v146, 1.0, v146
	v_add_f32_e32 v147, 1.0, v147
	v_add_f32_e32 v148, 1.0, v148
	v_add_f32_e32 v149, 1.0, v149
	v_rcp_f32_e32 v146, v146
	v_rcp_f32_e32 v147, v147
	v_rcp_f32_e32 v148, v148
	v_rcp_f32_e32 v149, v149
	v_mul_f32_e32 v146, v110, v146
	v_mul_f32_e32 v147, v111, v147
	v_mul_f32_e32 v148, v112, v148
	v_mul_f32_e32 v149, v113, v149
	v_mul_f32_e32 v106, v146, v106
	v_mul_f32_e32 v107, v147, v107
	v_mul_f32_e32 v108, v148, v108
	v_mul_f32_e32 v109, v149, v109
	v_mul_f32_e32 v146, 0xbfb8aa3b, v102
	v_mul_f32_e32 v147, 0xbfb8aa3b, v103
	v_mul_f32_e32 v148, 0xbfb8aa3b, v104
	v_mul_f32_e32 v149, 0xbfb8aa3b, v105
	v_exp_f32_e32 v146, v146
	v_exp_f32_e32 v147, v147
	v_exp_f32_e32 v148, v148
	v_exp_f32_e32 v149, v149
	v_add_f32_e32 v146, 1.0, v146
	v_add_f32_e32 v147, 1.0, v147
	v_add_f32_e32 v148, 1.0, v148
	v_add_f32_e32 v149, 1.0, v149
	v_rcp_f32_e32 v146, v146
	v_rcp_f32_e32 v147, v147
	v_rcp_f32_e32 v148, v148
	v_rcp_f32_e32 v149, v149
	v_mul_f32_e32 v146, v102, v146
	v_mul_f32_e32 v147, v103, v147
	v_mul_f32_e32 v148, v104, v148
	v_mul_f32_e32 v149, v105, v149
	v_mul_f32_e32 v102, v146, v98
	v_mul_f32_e32 v103, v147, v99
	v_mul_f32_e32 v104, v148, v100
	v_mul_f32_e32 v101, v149, v101
	v_or_b32_e32 v105, 16, v141
	v_cvt_pk_bf16_f32 v98, v106, v107
	v_cvt_pk_bf16_f32 v99, v108, v109
	v_cvt_pk_bf16_f32 v100, v102, v103
	v_mad_i64_i32 v[102:103], s[24:25], v105, s53, v[114:115]
	v_lshl_add_u64 v[102:103], v[102:103], 0, v[116:117]
	v_cvt_pk_bf16_f32 v101, v104, v101
	global_store_dwordx4 v[102:103], v[98:101], off
	s_nop 1
	v_mul_f32_e32 v146, 0xbfb8aa3b, v94
	v_mul_f32_e32 v147, 0xbfb8aa3b, v95
	v_mul_f32_e32 v148, 0xbfb8aa3b, v96
	v_mul_f32_e32 v149, 0xbfb8aa3b, v97
	v_exp_f32_e32 v146, v146
	v_exp_f32_e32 v147, v147
	v_exp_f32_e32 v148, v148
	v_exp_f32_e32 v149, v149
	v_add_f32_e32 v146, 1.0, v146
	v_add_f32_e32 v147, 1.0, v147
	v_add_f32_e32 v148, 1.0, v148
	v_add_f32_e32 v149, 1.0, v149
	v_rcp_f32_e32 v146, v146
	v_rcp_f32_e32 v147, v147
	v_rcp_f32_e32 v148, v148
	v_rcp_f32_e32 v149, v149
	v_mul_f32_e32 v146, v94, v146
	v_mul_f32_e32 v147, v95, v147
	v_mul_f32_e32 v148, v96, v148
	v_mul_f32_e32 v149, v97, v149
	v_mul_f32_e32 v90, v146, v90
	v_mul_f32_e32 v91, v147, v91
	v_mul_f32_e32 v92, v148, v92
	v_mul_f32_e32 v93, v149, v93
	v_mul_f32_e32 v146, 0xbfb8aa3b, v86
	v_mul_f32_e32 v147, 0xbfb8aa3b, v87
	v_mul_f32_e32 v148, 0xbfb8aa3b, v88
	v_mul_f32_e32 v149, 0xbfb8aa3b, v89
	v_exp_f32_e32 v146, v146
	v_exp_f32_e32 v147, v147
	v_exp_f32_e32 v148, v148
	v_exp_f32_e32 v149, v149
	v_add_f32_e32 v146, 1.0, v146
	v_add_f32_e32 v147, 1.0, v147
	v_add_f32_e32 v148, 1.0, v148
	v_add_f32_e32 v149, 1.0, v149
	v_rcp_f32_e32 v146, v146
	v_rcp_f32_e32 v147, v147
	v_rcp_f32_e32 v148, v148
	v_rcp_f32_e32 v149, v149
	v_mul_f32_e32 v146, v86, v146
	v_mul_f32_e32 v147, v87, v147
	v_mul_f32_e32 v148, v88, v148
	v_mul_f32_e32 v149, v89, v149
	v_mul_f32_e32 v86, v146, v82
	v_mul_f32_e32 v87, v147, v83
	v_mul_f32_e32 v88, v148, v84
	v_mul_f32_e32 v85, v149, v85
	v_or_b32_e32 v89, 32, v141
	v_cvt_pk_bf16_f32 v82, v90, v91
	v_cvt_pk_bf16_f32 v83, v92, v93
	v_cvt_pk_bf16_f32 v84, v86, v87
	v_mad_i64_i32 v[86:87], s[24:25], v89, s53, v[114:115]
	v_lshl_add_u64 v[86:87], v[86:87], 0, v[116:117]
	v_cvt_pk_bf16_f32 v85, v88, v85
	global_store_dwordx4 v[86:87], v[82:85], off
	s_nop 1
	v_mul_f32_e32 v146, 0xbfb8aa3b, v78
	v_mul_f32_e32 v147, 0xbfb8aa3b, v79
	v_mul_f32_e32 v148, 0xbfb8aa3b, v80
	v_mul_f32_e32 v149, 0xbfb8aa3b, v81
	v_exp_f32_e32 v146, v146
	v_exp_f32_e32 v147, v147
	v_exp_f32_e32 v148, v148
	v_exp_f32_e32 v149, v149
	v_add_f32_e32 v146, 1.0, v146
	v_add_f32_e32 v147, 1.0, v147
	v_add_f32_e32 v148, 1.0, v148
	v_add_f32_e32 v149, 1.0, v149
	v_rcp_f32_e32 v146, v146
	v_rcp_f32_e32 v147, v147
	v_rcp_f32_e32 v148, v148
	v_rcp_f32_e32 v149, v149
	v_mul_f32_e32 v146, v78, v146
	v_mul_f32_e32 v147, v79, v147
	v_mul_f32_e32 v148, v80, v148
	v_mul_f32_e32 v149, v81, v149
	v_mul_f32_e32 v74, v146, v74
	v_mul_f32_e32 v75, v147, v75
	v_mul_f32_e32 v76, v148, v76
	v_mul_f32_e32 v77, v149, v77
	v_mul_f32_e32 v146, 0xbfb8aa3b, v70
	v_mul_f32_e32 v147, 0xbfb8aa3b, v71
	v_mul_f32_e32 v148, 0xbfb8aa3b, v72
	v_mul_f32_e32 v149, 0xbfb8aa3b, v73
	v_exp_f32_e32 v146, v146
	v_exp_f32_e32 v147, v147
	v_exp_f32_e32 v148, v148
	v_exp_f32_e32 v149, v149
	v_add_f32_e32 v146, 1.0, v146
	v_add_f32_e32 v147, 1.0, v147
	v_add_f32_e32 v148, 1.0, v148
	v_add_f32_e32 v149, 1.0, v149
	v_rcp_f32_e32 v146, v146
	v_rcp_f32_e32 v147, v147
	v_rcp_f32_e32 v148, v148
	v_rcp_f32_e32 v149, v149
	v_mul_f32_e32 v146, v70, v146
	v_mul_f32_e32 v147, v71, v147
	v_mul_f32_e32 v148, v72, v148
	v_mul_f32_e32 v149, v73, v149
	v_mul_f32_e32 v70, v146, v66
	v_mul_f32_e32 v71, v147, v67
	v_mul_f32_e32 v72, v148, v68
	v_mul_f32_e32 v69, v149, v69
	v_or_b32_e32 v73, 48, v141
	v_cvt_pk_bf16_f32 v66, v74, v75
	v_cvt_pk_bf16_f32 v67, v76, v77
	v_cvt_pk_bf16_f32 v68, v70, v71
	v_mad_i64_i32 v[70:71], s[24:25], v73, s53, v[114:115]
	v_lshl_add_u64 v[70:71], v[70:71], 0, v[116:117]
	v_cvt_pk_bf16_f32 v69, v72, v69
	global_store_dwordx4 v[70:71], v[66:69], off
	s_nop 1
	v_mul_f32_e32 v146, 0xbfb8aa3b, v62
	v_mul_f32_e32 v147, 0xbfb8aa3b, v63
	v_mul_f32_e32 v148, 0xbfb8aa3b, v64
	v_mul_f32_e32 v149, 0xbfb8aa3b, v65
	v_exp_f32_e32 v146, v146
	v_exp_f32_e32 v147, v147
	v_exp_f32_e32 v148, v148
	v_exp_f32_e32 v149, v149
	v_add_f32_e32 v146, 1.0, v146
	v_add_f32_e32 v147, 1.0, v147
	v_add_f32_e32 v148, 1.0, v148
	v_add_f32_e32 v149, 1.0, v149
	v_rcp_f32_e32 v146, v146
	v_rcp_f32_e32 v147, v147
	v_rcp_f32_e32 v148, v148
	v_rcp_f32_e32 v149, v149
	v_mul_f32_e32 v146, v62, v146
	v_mul_f32_e32 v147, v63, v147
	v_mul_f32_e32 v148, v64, v148
	v_mul_f32_e32 v149, v65, v149
	v_mul_f32_e32 v58, v146, v58
	v_mul_f32_e32 v59, v147, v59
	v_mul_f32_e32 v60, v148, v60
	v_mul_f32_e32 v61, v149, v61
	v_mul_f32_e32 v146, 0xbfb8aa3b, v54
	v_mul_f32_e32 v147, 0xbfb8aa3b, v55
	v_mul_f32_e32 v148, 0xbfb8aa3b, v56
	v_mul_f32_e32 v149, 0xbfb8aa3b, v57
	v_exp_f32_e32 v146, v146
	v_exp_f32_e32 v147, v147
	v_exp_f32_e32 v148, v148
	v_exp_f32_e32 v149, v149
	v_add_f32_e32 v146, 1.0, v146
	v_add_f32_e32 v147, 1.0, v147
	v_add_f32_e32 v148, 1.0, v148
	v_add_f32_e32 v149, 1.0, v149
	v_rcp_f32_e32 v146, v146
	v_rcp_f32_e32 v147, v147
	v_rcp_f32_e32 v148, v148
	v_rcp_f32_e32 v149, v149
	v_mul_f32_e32 v146, v54, v146
	v_mul_f32_e32 v147, v55, v147
	v_mul_f32_e32 v148, v56, v148
	v_mul_f32_e32 v149, v57, v149
	v_mul_f32_e32 v54, v146, v50
	v_mul_f32_e32 v55, v147, v51
	v_mul_f32_e32 v56, v148, v52
	v_mul_f32_e32 v53, v149, v53
	v_add_u32_e32 v66, 0x80, v141
	v_cvt_pk_bf16_f32 v50, v58, v59
	v_cvt_pk_bf16_f32 v51, v60, v61
	v_cvt_pk_bf16_f32 v52, v54, v55
	v_mad_i64_i32 v[54:55], s[24:25], v66, s53, v[114:115]
	v_lshl_add_u64 v[54:55], v[54:55], 0, v[116:117]
	v_cvt_pk_bf16_f32 v53, v56, v53
	global_store_dwordx4 v[54:55], v[50:53], off
	s_nop 1
	v_mul_f32_e32 v146, 0xbfb8aa3b, v46
	v_mul_f32_e32 v147, 0xbfb8aa3b, v47
	v_mul_f32_e32 v148, 0xbfb8aa3b, v48
	v_mul_f32_e32 v149, 0xbfb8aa3b, v49
	v_exp_f32_e32 v146, v146
	v_exp_f32_e32 v147, v147
	v_exp_f32_e32 v148, v148
	v_exp_f32_e32 v149, v149
	v_add_f32_e32 v146, 1.0, v146
	v_add_f32_e32 v147, 1.0, v147
	v_add_f32_e32 v148, 1.0, v148
	v_add_f32_e32 v149, 1.0, v149
	v_rcp_f32_e32 v146, v146
	v_rcp_f32_e32 v147, v147
	v_rcp_f32_e32 v148, v148
	v_rcp_f32_e32 v149, v149
	v_mul_f32_e32 v146, v46, v146
	v_mul_f32_e32 v147, v47, v147
	v_mul_f32_e32 v148, v48, v148
	v_mul_f32_e32 v149, v49, v149
	v_mul_f32_e32 v42, v146, v42
	v_mul_f32_e32 v43, v147, v43
	v_mul_f32_e32 v44, v148, v44
	v_mul_f32_e32 v45, v149, v45
	v_mul_f32_e32 v146, 0xbfb8aa3b, v38
	v_mul_f32_e32 v147, 0xbfb8aa3b, v39
	v_mul_f32_e32 v148, 0xbfb8aa3b, v40
	v_mul_f32_e32 v149, 0xbfb8aa3b, v41
	v_exp_f32_e32 v146, v146
	v_exp_f32_e32 v147, v147
	v_exp_f32_e32 v148, v148
	v_exp_f32_e32 v149, v149
	v_add_f32_e32 v146, 1.0, v146
	v_add_f32_e32 v147, 1.0, v147
	v_add_f32_e32 v148, 1.0, v148
	v_add_f32_e32 v149, 1.0, v149
	v_rcp_f32_e32 v146, v146
	v_rcp_f32_e32 v147, v147
	v_rcp_f32_e32 v148, v148
	v_rcp_f32_e32 v149, v149
	v_mul_f32_e32 v146, v38, v146
	v_mul_f32_e32 v147, v39, v147
	v_mul_f32_e32 v148, v40, v148
	v_mul_f32_e32 v149, v41, v149
	v_mul_f32_e32 v38, v146, v34
	v_mul_f32_e32 v39, v147, v35
	v_mul_f32_e32 v40, v148, v36
	v_mul_f32_e32 v37, v149, v37
	v_add_u32_e32 v41, 0x90, v141
	v_cvt_pk_bf16_f32 v34, v42, v43
	v_cvt_pk_bf16_f32 v35, v44, v45
	v_cvt_pk_bf16_f32 v36, v38, v39
	v_mad_i64_i32 v[38:39], s[24:25], v41, s53, v[114:115]
	v_lshl_add_u64 v[38:39], v[38:39], 0, v[116:117]
	v_cvt_pk_bf16_f32 v37, v40, v37
	global_store_dwordx4 v[38:39], v[34:37], off
	s_nop 1
	v_mul_f32_e32 v146, 0xbfb8aa3b, v30
	v_mul_f32_e32 v147, 0xbfb8aa3b, v31
	v_mul_f32_e32 v148, 0xbfb8aa3b, v32
	v_mul_f32_e32 v149, 0xbfb8aa3b, v33
	v_exp_f32_e32 v146, v146
	v_exp_f32_e32 v147, v147
	v_exp_f32_e32 v148, v148
	v_exp_f32_e32 v149, v149
	v_add_f32_e32 v146, 1.0, v146
	v_add_f32_e32 v147, 1.0, v147
	v_add_f32_e32 v148, 1.0, v148
	v_add_f32_e32 v149, 1.0, v149
	v_rcp_f32_e32 v146, v146
	v_rcp_f32_e32 v147, v147
	v_rcp_f32_e32 v148, v148
	v_rcp_f32_e32 v149, v149
	v_mul_f32_e32 v146, v30, v146
	v_mul_f32_e32 v147, v31, v147
	v_mul_f32_e32 v148, v32, v148
	v_mul_f32_e32 v149, v33, v149
	v_mul_f32_e32 v26, v146, v26
	v_mul_f32_e32 v27, v147, v27
	v_mul_f32_e32 v28, v148, v28
	v_mul_f32_e32 v29, v149, v29
	v_mul_f32_e32 v146, 0xbfb8aa3b, v22
	v_mul_f32_e32 v147, 0xbfb8aa3b, v23
	v_mul_f32_e32 v148, 0xbfb8aa3b, v24
	v_mul_f32_e32 v149, 0xbfb8aa3b, v25
	v_exp_f32_e32 v146, v146
	v_exp_f32_e32 v147, v147
	v_exp_f32_e32 v148, v148
	v_exp_f32_e32 v149, v149
	v_add_f32_e32 v146, 1.0, v146
	v_add_f32_e32 v147, 1.0, v147
	v_add_f32_e32 v148, 1.0, v148
	v_add_f32_e32 v149, 1.0, v149
	v_rcp_f32_e32 v146, v146
	v_rcp_f32_e32 v147, v147
	v_rcp_f32_e32 v148, v148
	v_rcp_f32_e32 v149, v149
	v_mul_f32_e32 v146, v22, v146
	v_mul_f32_e32 v147, v23, v147
	v_mul_f32_e32 v148, v24, v148
	v_mul_f32_e32 v149, v25, v149
	v_mul_f32_e32 v22, v146, v18
	v_mul_f32_e32 v23, v147, v19
	v_mul_f32_e32 v24, v148, v20
	v_mul_f32_e32 v21, v149, v21
	v_add_u32_e32 v25, 0xa0, v141
	v_cvt_pk_bf16_f32 v18, v26, v27
	v_cvt_pk_bf16_f32 v19, v28, v29
	v_cvt_pk_bf16_f32 v20, v22, v23
	v_mad_i64_i32 v[22:23], s[24:25], v25, s53, v[114:115]
	v_lshl_add_u64 v[22:23], v[22:23], 0, v[116:117]
	v_cvt_pk_bf16_f32 v21, v24, v21
	global_store_dwordx4 v[22:23], v[18:21], off
	s_nop 1
	v_mul_f32_e32 v146, 0xbfb8aa3b, v14
	v_mul_f32_e32 v147, 0xbfb8aa3b, v15
	v_mul_f32_e32 v148, 0xbfb8aa3b, v16
	v_mul_f32_e32 v149, 0xbfb8aa3b, v17
	v_exp_f32_e32 v146, v146
	v_exp_f32_e32 v147, v147
	v_exp_f32_e32 v148, v148
	v_exp_f32_e32 v149, v149
	v_add_f32_e32 v146, 1.0, v146
	v_add_f32_e32 v147, 1.0, v147
	v_add_f32_e32 v148, 1.0, v148
	v_add_f32_e32 v149, 1.0, v149
	v_rcp_f32_e32 v146, v146
	v_rcp_f32_e32 v147, v147
	v_rcp_f32_e32 v148, v148
	v_rcp_f32_e32 v149, v149
	v_mul_f32_e32 v146, v14, v146
	v_mul_f32_e32 v147, v15, v147
	v_mul_f32_e32 v148, v16, v148
	v_mul_f32_e32 v149, v17, v149
	v_mul_f32_e32 v10, v146, v10
	v_mul_f32_e32 v11, v147, v11
	v_mul_f32_e32 v12, v148, v12
	v_mul_f32_e32 v13, v149, v13
	v_mul_f32_e32 v146, 0xbfb8aa3b, v6
	v_mul_f32_e32 v147, 0xbfb8aa3b, v7
	v_mul_f32_e32 v148, 0xbfb8aa3b, v8
	v_mul_f32_e32 v149, 0xbfb8aa3b, v9
	v_exp_f32_e32 v146, v146
	v_exp_f32_e32 v147, v147
	v_exp_f32_e32 v148, v148
	v_exp_f32_e32 v149, v149
	v_add_f32_e32 v146, 1.0, v146
	v_add_f32_e32 v147, 1.0, v147
	v_add_f32_e32 v148, 1.0, v148
	v_add_f32_e32 v149, 1.0, v149
	v_rcp_f32_e32 v146, v146
	v_rcp_f32_e32 v147, v147
	v_rcp_f32_e32 v148, v148
	v_rcp_f32_e32 v149, v149
	v_mul_f32_e32 v146, v6, v146
	v_mul_f32_e32 v147, v7, v147
	v_mul_f32_e32 v148, v8, v148
	v_mul_f32_e32 v149, v9, v149
	v_mul_f32_e32 v6, v146, v2
	v_mul_f32_e32 v7, v147, v3
	v_mul_f32_e32 v8, v148, v4
	v_mul_f32_e32 v5, v149, v5
	v_add_u32_e32 v9, 0xb0, v141
	v_cvt_pk_bf16_f32 v2, v10, v11
	v_cvt_pk_bf16_f32 v3, v12, v13
	v_cvt_pk_bf16_f32 v4, v6, v7
	v_mad_i64_i32 v[6:7], s[24:25], v9, s53, v[114:115]
	v_lshl_add_u64 v[6:7], v[6:7], 0, v[116:117]
	s_mov_b64 s[24:25], -1
	v_cvt_pk_bf16_f32 v5, v8, v5
	global_store_dwordx4 v[6:7], v[2:5], off
	s_cbranch_vccnz .LBB0_1056
	s_andn2_b64 vcc, exec, s[8:9]
	s_cbranch_vccnz .LBB0_1055
	s_barrier
	s_branch .LBB0_1055
